# GEMM tile prologues: accumulators cleared while the first slices are in flight (counted vmcnt for the store-data WAR) instead of after slice 0 behind a full vmcnt(0)
# speedup vs baseline: 1.0534x; 1.0066x over previous
.LBB0_115:
	s_andn2_b64 vcc, exec, s[22:23]
	s_cbranch_vccnz .LBB0_138
	v_readlane_b32 s22, v254, 44
	v_readlane_b32 s23, v254, 45
	s_andn2_b64 vcc, exec, s[22:23]
	s_cbranch_vccnz .LBB0_138
	v_mov_b32_e32 v8, v202
	v_readlane_b32 s8, v254, 48
	v_bfe_u32 v135, v8, 4, 2
	v_bfe_u32 v4, v8, 2, 4
	v_ashrrev_i32_e32 v136, 6, v8
	v_bitop3_b32 v0, v135, v8, 3 bitop3:0x78
	v_or_b32_e32 v9, s8, v4
	v_readlane_b32 s8, v254, 46
	v_lshlrev_b32_e32 v0, 4, v0
	v_cmp_gt_i32_e32 vcc, 16, v136
	v_or_b32_e32 v10, s8, v4
	v_lshl_add_u64 v[2:3], s[20:21], 0, v[0:1]
	v_lshl_add_u64 v[4:5], s[46:47], 0, v[0:1]
	v_lshlrev_b32_e32 v0, 4, v136
	v_cndmask_b32_e32 v11, v9, v10, vcc
	v_cndmask_b32_e32 v7, v3, v5, vcc
	v_cndmask_b32_e32 v6, v2, v4, vcc
	v_add_u32_e32 v11, v11, v0
	v_cmp_gt_i32_e32 vcc, 8, v136
	v_mad_i64_i32 v[126:127], s[20:21], v11, s5, v[6:7]
	s_nop 0
	v_cndmask_b32_e32 v11, v9, v10, vcc
	s_movk_i32 s8, 0x80
	v_cndmask_b32_e32 v7, v3, v5, vcc
	v_cndmask_b32_e32 v6, v2, v4, vcc
	v_add3_u32 v11, v0, v11, s8
	v_cmp_gt_i32_e32 vcc, 0, v136
	v_mad_i64_i32 v[128:129], s[20:21], v11, s5, v[6:7]
	s_nop 0
	v_cndmask_b32_e32 v6, v9, v10, vcc
	s_movk_i32 s8, 0x100
	v_and_b32_e32 v134, 63, v8
	v_cndmask_b32_e32 v3, v3, v5, vcc
	v_cndmask_b32_e32 v2, v2, v4, vcc
	v_add3_u32 v0, v0, v6, s8
	v_mad_i64_i32 v[130:131], s[20:21], v0, s5, v[2:3]
	v_lshlrev_b32_e32 v0, 4, v134
	v_lshl_or_b32 v137, v136, 10, v0
	v_add_u32_e32 v0, 0x2000, v137
	v_readfirstlane_b32 s8, v137
	s_mov_b32 m0, s8
	v_readfirstlane_b32 s8, v0
	v_add_u32_e32 v0, 0x4000, v137
	s_barrier
	global_load_lds_dwordx4 v[126:127], off
	s_mov_b32 m0, s8
	v_readfirstlane_b32 s8, v0
	v_add_u32_e32 v0, 0x6000, v137
	global_load_lds_dwordx4 v[128:129], off
	s_mov_b32 m0, s8
	v_readfirstlane_b32 s8, v0
	v_add_u32_e32 v0, 0x8000, v137
	global_load_lds_dwordx4 v[130:131], off
	v_lshl_add_u64 v[2:3], v[126:127], 0, 64
	s_mov_b32 m0, s8
	v_readfirstlane_b32 s8, v0
	v_add_u32_e32 v0, 0xa000, v137
	global_load_lds_dwordx4 v[2:3], off
	v_lshl_add_u64 v[2:3], v[128:129], 0, 64
	s_mov_b32 m0, s8
	v_readfirstlane_b32 s8, v0
	v_add_u32_e32 v0, 0xc000, v137
	global_load_lds_dwordx4 v[2:3], off
	v_lshl_add_u64 v[2:3], v[130:131], 0, 64
	s_mov_b32 m0, s8
	v_readfirstlane_b32 s8, v0
	v_add_u32_e32 v0, 0xe000, v137
	global_load_lds_dwordx4 v[2:3], off
	v_lshl_add_u64 v[2:3], v[126:127], 0, s[10:11]
	s_mov_b32 m0, s8
	v_readfirstlane_b32 s8, v0
	v_add_u32_e32 v0, 0x10000, v137
	global_load_lds_dwordx4 v[2:3], off
	v_lshl_add_u64 v[2:3], v[128:129], 0, s[10:11]
	s_mov_b32 m0, s8
	v_readfirstlane_b32 s8, v0
	global_load_lds_dwordx4 v[2:3], off
	v_lshl_add_u64 v[2:3], v[130:131], 0, s[10:11]
	s_mov_b32 m0, s8
	v_and_b32_e32 v138, 15, v8
	global_load_lds_dwordx4 v[2:3], off
	v_readfirstlane_b32 s90, v126
	v_readfirstlane_b32 s91, v127
	v_readfirstlane_b32 s92, v130
	v_readfirstlane_b32 s93, v131
	v_readfirstlane_b32 s88, v137
	s_nop 1
	v_subrev_u32_e32 v126, s90, v126
	v_subrev_u32_e32 v128, s90, v128
	v_subrev_u32_e32 v130, s92, v130
	s_add_u32 s90, s90, 0xc0
	s_addc_u32 s91, s91, 0
	s_add_u32 s92, s92, 0xc0
	s_addc_u32 s93, s93, 0
	v_bfe_u32 v2, v8, 2, 2
	v_and_b32_e32 v139, 1, v136
	v_xor_b32_e32 v2, v135, v2
	v_lshlrev_b32_e32 v3, 6, v138
	v_ashrrev_i32_e32 v0, 7, v8
	v_lshl_or_b32 v2, v2, 4, v3
	v_lshlrev_b32_e32 v3, 12, v139
	s_movk_i32 s8, 0x4000
	s_waitcnt vmcnt(9)
	v_mov_b32_e32 v19, 0
	v_mov_b32_e32 v20, 0
	v_mov_b32_e32 v21, 0
	v_mov_b32_e32 v30, 0
	v_mov_b32_e32 v31, 0
	v_mov_b32_e32 v32, 0
	v_mov_b32_e32 v33, 0
	v_mov_b32_e32 v35, 0
	v_mov_b32_e32 v36, 0
	v_mov_b32_e32 v37, 0
	v_mov_b32_e32 v38, 0
	v_mov_b32_e32 v39, 0
	v_mov_b32_e32 v40, 0
	v_mov_b32_e32 v41, 0
	v_mov_b32_e32 v42, 0
	v_mov_b32_e32 v43, 0
	v_mov_b32_e32 v44, 0
	v_mov_b32_e32 v45, 0
	v_mov_b32_e32 v46, 0
	v_mov_b32_e32 v47, 0
	v_mov_b32_e32 v48, 0
	v_mov_b32_e32 v49, 0
	v_mov_b32_e32 v50, 0
	v_mov_b32_e32 v51, 0
	v_mov_b32_e32 v52, 0
	v_mov_b32_e32 v53, 0
	v_mov_b32_e32 v54, 0
	v_mov_b32_e32 v55, 0
	v_mov_b32_e32 v56, 0
	v_mov_b32_e32 v57, 0
	v_mov_b32_e32 v58, 0
	v_mov_b32_e32 v59, 0
	v_mov_b32_e32 v60, 0
	v_mov_b32_e32 v61, 0
	v_mov_b32_e32 v62, 0
	v_mov_b32_e32 v63, 0
	v_mov_b32_e32 v64, 0
	v_mov_b32_e32 v65, 0
	v_mov_b32_e32 v66, 0
	v_mov_b32_e32 v67, 0
	v_mov_b32_e32 v68, 0
	v_mov_b32_e32 v69, 0
	v_mov_b32_e32 v70, 0
	v_mov_b32_e32 v71, 0
	v_mov_b32_e32 v72, 0
	v_mov_b32_e32 v73, 0
	v_mov_b32_e32 v74, 0
	v_mov_b32_e32 v75, 0
	v_mov_b32_e32 v76, 0
	v_mov_b32_e32 v77, 0
	v_mov_b32_e32 v78, 0
	v_mov_b32_e32 v79, 0
	v_mov_b32_e32 v80, 0
	v_mov_b32_e32 v81, 0
	v_mov_b32_e32 v82, 0
	v_mov_b32_e32 v83, 0
	v_mov_b32_e32 v84, 0
	v_mov_b32_e32 v85, 0
	v_mov_b32_e32 v86, 0
	v_mov_b32_e32 v87, 0
	v_mov_b32_e32 v88, 0
	v_mov_b32_e32 v89, 0
	v_mov_b32_e32 v90, 0
	v_mov_b32_e32 v91, 0
	v_mov_b32_e32 v92, 0
	v_mov_b32_e32 v93, 0
	v_mov_b32_e32 v94, 0
	v_mov_b32_e32 v95, 0
	v_mov_b32_e32 v96, 0
	v_mov_b32_e32 v97, 0
	v_mov_b32_e32 v98, 0
	v_mov_b32_e32 v99, 0
	v_mov_b32_e32 v100, 0
	v_mov_b32_e32 v101, 0
	v_mov_b32_e32 v102, 0
	v_mov_b32_e32 v103, 0
	v_mov_b32_e32 v104, 0
	v_mov_b32_e32 v105, 0
	s_waitcnt vmcnt(6)
	v_lshl_or_b32 v140, v0, 12, v2
	v_or3_b32 v141, v3, v2, s8
	s_waitcnt lgkmcnt(0)
	s_barrier
	ds_read_b128 v[2:5], v140
	ds_read_b128 v[6:9], v140 offset:1024
	ds_read_b128 v[10:13], v140 offset:2048
	ds_read_b128 v[14:17], v140 offset:3072
	ds_read_b128 v[26:29], v141
	ds_read_b128 v[22:25], v141 offset:1024
	v_cmp_lt_i32_e32 vcc, 3, v136
	s_and_saveexec_b64 s[20:21], vcc
	s_cbranch_execz .LBB0_119
	s_barrier
.LBB0_119:
	s_or_b64 exec, exec, s[20:21]
	v_mov_b32_e32 v18, 0
	v_mov_b32_e32 v34, 0
	v_add_u32_e32 v142, 0x800, v141
	s_mov_b64 s[20:21], 0
	s_mov_b32 s8, 3
	s_branch .LBB0_121

.LBB0_179:
	s_lshl_b32 s17, s8, 6
	v_mov_b32_e32 v10, v202
	s_and_b32 s17, s17, 0x1f00
	s_add_i32 s19, s17, 0xffffff00
	v_bfe_u32 v196, v10, 4, 2
	v_ashrrev_i32_e32 v197, 6, v10
	v_bfe_u32 v4, v10, 2, 4
	v_bitop3_b32 v0, v196, v10, 3 bitop3:0x78
	v_readlane_b32 s20, v254, 49
	v_or_b32_e32 v11, s19, v4
	v_lshlrev_b32_e32 v0, 4, v0
	v_or_b32_e32 v12, s22, v4
	v_readlane_b32 s21, v254, 50
	v_cmp_gt_i32_e32 vcc, 16, v197
	v_lshl_add_u64 v[2:3], s[40:41], 0, v[0:1]
	v_lshl_add_u64 v[4:5], s[20:21], 0, v[0:1]
	v_lshlrev_b32_e32 v0, 4, v197
	v_cndmask_b32_e32 v8, v11, v12, vcc
	v_add_u32_e32 v8, v8, v0
	v_ashrrev_i32_e32 v9, 31, v8
	v_cndmask_b32_e32 v7, v3, v5, vcc
	v_cndmask_b32_e32 v6, v2, v4, vcc
	v_lshlrev_b64 v[8:9], 11, v[8:9]
	v_cmp_gt_i32_e32 vcc, 8, v197
	v_lshl_add_u64 v[186:187], v[6:7], 0, v[8:9]
	s_movk_i32 s19, 0x80
	v_cndmask_b32_e32 v8, v11, v12, vcc
	v_add3_u32 v8, v0, v8, s19
	v_ashrrev_i32_e32 v9, 31, v8
	v_cndmask_b32_e32 v7, v3, v5, vcc
	v_cndmask_b32_e32 v6, v2, v4, vcc
	v_lshlrev_b64 v[8:9], 11, v[8:9]
	v_cmp_gt_i32_e32 vcc, 0, v197
	v_lshl_add_u64 v[188:189], v[6:7], 0, v[8:9]
	s_movk_i32 s19, 0x100
	v_cndmask_b32_e32 v8, v11, v12, vcc
	v_add3_u32 v8, v0, v8, s19
	v_ashrrev_i32_e32 v9, 31, v8
	v_cndmask_b32_e32 v7, v3, v5, vcc
	v_cndmask_b32_e32 v6, v2, v4, vcc
	v_lshlrev_b64 v[8:9], 11, v[8:9]
	v_cmp_gt_i32_e32 vcc, -8, v197
	v_and_b32_e32 v194, 63, v10
	v_lshl_add_u64 v[190:191], v[6:7], 0, v[8:9]
	v_cndmask_b32_e32 v6, v11, v12, vcc
	s_movk_i32 s19, 0x180
	v_cndmask_b32_e32 v2, v2, v4, vcc
	v_add3_u32 v4, v0, v6, s19
	v_lshlrev_b32_e32 v0, 4, v194
	v_lshl_or_b32 v198, v197, 10, v0
	v_add_u32_e32 v0, 0x2000, v198
	v_readfirstlane_b32 s19, v198
	s_mov_b32 m0, s19
	v_readfirstlane_b32 s19, v0
	v_add_u32_e32 v0, 0x4000, v198
	v_cndmask_b32_e32 v3, v3, v5, vcc
	v_ashrrev_i32_e32 v5, 31, v4
	s_barrier
	global_load_lds_dwordx4 v[186:187], off
	s_mov_b32 m0, s19
	v_readfirstlane_b32 s19, v0
	v_add_u32_e32 v0, 0x6000, v198
	v_lshlrev_b64 v[4:5], 11, v[4:5]
	global_load_lds_dwordx4 v[188:189], off
	s_mov_b32 m0, s19
	v_readfirstlane_b32 s19, v0
	v_add_u32_e32 v0, 0x8000, v198
	v_lshl_add_u64 v[192:193], v[2:3], 0, v[4:5]
	global_load_lds_dwordx4 v[190:191], off
	s_mov_b32 m0, s19
	v_readfirstlane_b32 s19, v0
	v_add_u32_e32 v0, 0xa000, v198
	global_load_lds_dwordx4 v[192:193], off
	v_lshl_add_u64 v[2:3], v[186:187], 0, 64
	s_mov_b32 m0, s19
	v_readfirstlane_b32 s19, v0
	v_add_u32_e32 v0, 0xc000, v198
	global_load_lds_dwordx4 v[2:3], off
	v_lshl_add_u64 v[2:3], v[188:189], 0, 64
	s_mov_b32 m0, s19
	v_readfirstlane_b32 s19, v0
	v_add_u32_e32 v0, 0xe000, v198
	global_load_lds_dwordx4 v[2:3], off
	v_lshl_add_u64 v[2:3], v[190:191], 0, 64
	s_mov_b32 m0, s19
	v_readfirstlane_b32 s19, v0
	v_add_u32_e32 v0, 0x10000, v198
	global_load_lds_dwordx4 v[2:3], off
	v_lshl_add_u64 v[2:3], v[192:193], 0, 64
	s_mov_b32 m0, s19
	v_readfirstlane_b32 s19, v0
	v_add_u32_e32 v0, 0x12000, v198
	global_load_lds_dwordx4 v[2:3], off
	v_lshl_add_u64 v[2:3], v[186:187], 0, s[10:11]
	s_mov_b32 m0, s19
	v_readfirstlane_b32 s19, v0
	v_add_u32_e32 v0, 0x14000, v198
	global_load_lds_dwordx4 v[2:3], off
	v_lshl_add_u64 v[2:3], v[188:189], 0, s[10:11]
	s_mov_b32 m0, s19
	v_readfirstlane_b32 s19, v0
	v_add_u32_e32 v0, 0x16000, v198
	global_load_lds_dwordx4 v[2:3], off
	v_lshl_add_u64 v[2:3], v[190:191], 0, s[10:11]
	s_mov_b32 m0, s19
	v_readfirstlane_b32 s19, v0
	global_load_lds_dwordx4 v[2:3], off
	v_lshl_add_u64 v[2:3], v[192:193], 0, s[10:11]
	s_mov_b32 m0, s19
	v_and_b32_e32 v199, 15, v10
	global_load_lds_dwordx4 v[2:3], off
	v_readfirstlane_b32 s90, v186
	v_readfirstlane_b32 s91, v187
	v_readfirstlane_b32 s92, v190
	v_readfirstlane_b32 s93, v191
	v_readfirstlane_b32 s88, v198
	s_nop 1
	v_subrev_u32_e32 v186, s90, v186
	v_subrev_u32_e32 v188, s90, v188
	v_subrev_u32_e32 v190, s92, v190
	v_subrev_u32_e32 v192, s92, v192
	s_add_u32 s90, s90, 0xc0
	s_addc_u32 s91, s91, 0
	s_add_u32 s92, s92, 0xc0
	s_addc_u32 s93, s93, 0
	v_bfe_u32 v2, v10, 2, 2
	v_xor_b32_e32 v2, v196, v2
	v_lshlrev_b32_e32 v3, 6, v199
	v_ashrrev_i32_e32 v0, 7, v10
	v_and_b32_e32 v195, 1, v197
	v_lshl_or_b32 v2, v2, 4, v3
	s_waitcnt vmcnt(12)
	v_mov_b32_e32 v4, 0
	v_mov_b32_e32 v5, 0
	v_mov_b32_e32 v6, 0
	v_mov_b32_e32 v7, 0
	v_mov_b32_e32 v8, 0
	v_mov_b32_e32 v9, 0
	v_mov_b32_e32 v10, 0
	v_mov_b32_e32 v11, 0
	v_mov_b32_e32 v12, 0
	v_mov_b32_e32 v13, 0
	v_mov_b32_e32 v14, 0
	v_mov_b32_e32 v15, 0
	v_mov_b32_e32 v16, 0
	v_mov_b32_e32 v17, 0
	v_mov_b32_e32 v18, 0
	v_mov_b32_e32 v19, 0
	v_mov_b32_e32 v20, 0
	v_mov_b32_e32 v21, 0
	v_mov_b32_e32 v22, 0
	v_mov_b32_e32 v23, 0
	v_mov_b32_e32 v24, 0
	v_mov_b32_e32 v25, 0
	v_mov_b32_e32 v26, 0
	v_mov_b32_e32 v27, 0
	v_mov_b32_e32 v28, 0
	v_mov_b32_e32 v29, 0
	v_mov_b32_e32 v30, 0
	v_mov_b32_e32 v31, 0
	v_mov_b32_e32 v32, 0
	v_mov_b32_e32 v33, 0
	v_mov_b32_e32 v34, 0
	v_mov_b32_e32 v35, 0
	v_mov_b32_e32 v36, 0
	v_mov_b32_e32 v37, 0
	v_mov_b32_e32 v38, 0
	v_mov_b32_e32 v39, 0
	v_mov_b32_e32 v40, 0
	v_mov_b32_e32 v41, 0
	v_mov_b32_e32 v42, 0
	v_mov_b32_e32 v43, 0
	v_mov_b32_e32 v44, 0
	v_mov_b32_e32 v45, 0
	v_mov_b32_e32 v46, 0
	v_mov_b32_e32 v47, 0
	v_mov_b32_e32 v48, 0
	v_mov_b32_e32 v49, 0
	v_mov_b32_e32 v50, 0
	v_mov_b32_e32 v51, 0
	v_mov_b32_e32 v52, 0
	v_mov_b32_e32 v53, 0
	v_mov_b32_e32 v54, 0
	v_mov_b32_e32 v55, 0
	v_mov_b32_e32 v56, 0
	v_mov_b32_e32 v57, 0
	v_mov_b32_e32 v58, 0
	v_mov_b32_e32 v59, 0
	v_mov_b32_e32 v60, 0
	v_mov_b32_e32 v61, 0
	v_mov_b32_e32 v62, 0
	v_mov_b32_e32 v63, 0
	v_mov_b32_e32 v64, 0
	v_mov_b32_e32 v65, 0
	v_mov_b32_e32 v66, 0
	v_mov_b32_e32 v67, 0
	v_mov_b32_e32 v68, 0
	v_mov_b32_e32 v69, 0
	v_mov_b32_e32 v70, 0
	v_mov_b32_e32 v71, 0
	v_mov_b32_e32 v72, 0
	v_mov_b32_e32 v73, 0
	v_mov_b32_e32 v74, 0
	v_mov_b32_e32 v75, 0
	v_mov_b32_e32 v76, 0
	v_mov_b32_e32 v77, 0
	v_mov_b32_e32 v78, 0
	v_mov_b32_e32 v79, 0
	v_mov_b32_e32 v80, 0
	v_mov_b32_e32 v81, 0
	v_mov_b32_e32 v82, 0
	v_mov_b32_e32 v83, 0
	v_mov_b32_e32 v84, 0
	v_mov_b32_e32 v85, 0
	v_mov_b32_e32 v86, 0
	v_mov_b32_e32 v87, 0
	v_mov_b32_e32 v88, 0
	v_mov_b32_e32 v89, 0
	v_mov_b32_e32 v90, 0
	v_mov_b32_e32 v91, 0
	v_mov_b32_e32 v92, 0
	v_mov_b32_e32 v93, 0
	v_mov_b32_e32 v94, 0
	v_mov_b32_e32 v95, 0
	v_mov_b32_e32 v96, 0
	v_mov_b32_e32 v97, 0
	v_mov_b32_e32 v98, 0
	v_mov_b32_e32 v99, 0
	v_mov_b32_e32 v100, 0
	v_mov_b32_e32 v101, 0
	v_mov_b32_e32 v102, 0
	v_mov_b32_e32 v103, 0
	v_mov_b32_e32 v104, 0
	v_mov_b32_e32 v105, 0
	v_mov_b32_e32 v106, 0
	v_mov_b32_e32 v107, 0
	v_mov_b32_e32 v108, 0
	v_mov_b32_e32 v109, 0
	v_mov_b32_e32 v110, 0
	v_mov_b32_e32 v111, 0
	v_mov_b32_e32 v112, 0
	v_mov_b32_e32 v113, 0
	v_mov_b32_e32 v114, 0
	v_mov_b32_e32 v115, 0
	v_mov_b32_e32 v116, 0
	v_mov_b32_e32 v117, 0
	v_mov_b32_e32 v118, 0
	v_mov_b32_e32 v119, 0
	v_mov_b32_e32 v120, 0
	v_mov_b32_e32 v121, 0
	v_mov_b32_e32 v154, 0
	v_mov_b32_e32 v155, 0
	v_mov_b32_e32 v156, 0
	v_mov_b32_e32 v157, 0
	v_mov_b32_e32 v158, 0
	v_mov_b32_e32 v159, 0
	v_mov_b32_e32 v160, 0
	v_mov_b32_e32 v161, 0
	s_waitcnt vmcnt(8)
	v_lshl_or_b32 v200, v0, 12, v2
	v_lshlrev_b32_e32 v3, 13, v195
	s_movk_i32 s19, 0x4000
	s_waitcnt lgkmcnt(0)
	s_barrier
	ds_read_b128 v[122:125], v200
	ds_read_b128 v[126:129], v200 offset:1024
	ds_read_b128 v[130:133], v200 offset:2048
	ds_read_b128 v[134:137], v200 offset:3072
	v_or3_b32 v201, v3, v2, s19
	ds_read_b128 v[150:153], v201
	ds_read_b128 v[146:149], v201 offset:1024
	ds_read_b128 v[142:145], v201 offset:2048
	ds_read_b128 v[138:141], v201 offset:3072
	v_cmp_lt_i32_e32 vcc, 3, v197
	s_and_saveexec_b64 s[20:21], vcc
	s_cbranch_execz .LBB0_181
	s_barrier
.LBB0_181:
	s_or_b64 exec, exec, s[20:21]
	v_mov_b32_e32 v2, 0
	v_add_u32_e32 v230, 0x1000, v201
	s_mov_b32 s19, 0
	s_mov_b64 s[20:21], 0
	s_mov_b32 s31, 0x18000
	v_mov_b32_e32 v3, v2
	s_branch .LBB0_183

.LBB0_285:
	s_andn2_b64 vcc, exec, s[22:23]
	s_cbranch_vccnz .LBB0_372
	v_readlane_b32 s22, v254, 44
	v_readlane_b32 s23, v254, 45
	s_andn2_b64 vcc, exec, s[22:23]
	s_cbranch_vccnz .LBB0_372
	v_mov_b32_e32 v10, v202
	v_readlane_b32 s8, v254, 48
	v_bfe_u32 v135, v10, 4, 2
	v_bitop3_b32 v0, v135, v10, 3 bitop3:0x78
	v_bfe_u32 v4, v10, 2, 4
	v_lshlrev_b32_e32 v0, 4, v0
	v_ashrrev_i32_e32 v136, 6, v10
	v_or_b32_e32 v11, s8, v4
	v_lshl_add_u64 v[2:3], s[20:21], 0, v[0:1]
	v_readlane_b32 s8, v254, 46
	v_readlane_b32 s20, v254, 49
	v_readlane_b32 s21, v254, 50
	v_or_b32_e32 v12, s8, v4
	v_cmp_gt_i32_e32 vcc, 16, v136
	v_lshl_add_u64 v[4:5], s[20:21], 0, v[0:1]
	v_lshlrev_b32_e32 v0, 4, v136
	v_cndmask_b32_e32 v8, v11, v12, vcc
	v_add_u32_e32 v8, v8, v0
	v_ashrrev_i32_e32 v9, 31, v8
	v_cndmask_b32_e32 v7, v3, v5, vcc
	v_cndmask_b32_e32 v6, v2, v4, vcc
	v_lshlrev_b64 v[8:9], 11, v[8:9]
	v_cmp_gt_i32_e32 vcc, 8, v136
	v_lshl_add_u64 v[126:127], v[6:7], 0, v[8:9]
	s_movk_i32 s8, 0x80
	v_cndmask_b32_e32 v8, v11, v12, vcc
	v_add3_u32 v8, v0, v8, s8
	v_ashrrev_i32_e32 v9, 31, v8
	v_cndmask_b32_e32 v7, v3, v5, vcc
	v_cndmask_b32_e32 v6, v2, v4, vcc
	v_lshlrev_b64 v[8:9], 11, v[8:9]
	v_cmp_gt_i32_e32 vcc, 0, v136
	v_and_b32_e32 v134, 63, v10
	v_lshl_add_u64 v[128:129], v[6:7], 0, v[8:9]
	v_cndmask_b32_e32 v6, v11, v12, vcc
	s_movk_i32 s8, 0x100
	v_cndmask_b32_e32 v2, v2, v4, vcc
	v_add3_u32 v4, v0, v6, s8
	v_lshlrev_b32_e32 v0, 4, v134
	v_lshl_or_b32 v137, v136, 10, v0
	v_add_u32_e32 v0, 0x2000, v137
	v_readfirstlane_b32 s8, v137
	v_cndmask_b32_e32 v3, v3, v5, vcc
	v_ashrrev_i32_e32 v5, 31, v4
	s_mov_b32 m0, s8
	v_readfirstlane_b32 s8, v0
	v_add_u32_e32 v0, 0x4000, v137
	v_lshlrev_b64 v[4:5], 11, v[4:5]
	s_barrier
	global_load_lds_dwordx4 v[126:127], off
	s_mov_b32 m0, s8
	v_readfirstlane_b32 s8, v0
	v_add_u32_e32 v0, 0x6000, v137
	v_lshl_add_u64 v[130:131], v[2:3], 0, v[4:5]
	global_load_lds_dwordx4 v[128:129], off
	s_mov_b32 m0, s8
	v_readfirstlane_b32 s8, v0
	v_add_u32_e32 v0, 0x8000, v137
	global_load_lds_dwordx4 v[130:131], off
	v_lshl_add_u64 v[2:3], v[126:127], 0, 64
	s_mov_b32 m0, s8
	v_readfirstlane_b32 s8, v0
	v_add_u32_e32 v0, 0xa000, v137
	global_load_lds_dwordx4 v[2:3], off
	v_lshl_add_u64 v[2:3], v[128:129], 0, 64
	s_mov_b32 m0, s8
	v_readfirstlane_b32 s8, v0
	v_add_u32_e32 v0, 0xc000, v137
	global_load_lds_dwordx4 v[2:3], off
	v_lshl_add_u64 v[2:3], v[130:131], 0, 64
	s_mov_b32 m0, s8
	v_readfirstlane_b32 s8, v0
	v_add_u32_e32 v0, 0xe000, v137
	global_load_lds_dwordx4 v[2:3], off
	v_lshl_add_u64 v[2:3], v[126:127], 0, s[10:11]
	s_mov_b32 m0, s8
	v_readfirstlane_b32 s8, v0
	v_add_u32_e32 v0, 0x10000, v137
	global_load_lds_dwordx4 v[2:3], off
	v_lshl_add_u64 v[2:3], v[128:129], 0, s[10:11]
	s_mov_b32 m0, s8
	v_readfirstlane_b32 s8, v0
	global_load_lds_dwordx4 v[2:3], off
	v_lshl_add_u64 v[2:3], v[130:131], 0, s[10:11]
	s_mov_b32 m0, s8
	v_and_b32_e32 v138, 15, v10
	global_load_lds_dwordx4 v[2:3], off
	v_readfirstlane_b32 s44, v126
	v_readfirstlane_b32 s45, v127
	v_readfirstlane_b32 s30, v130
	v_readfirstlane_b32 s31, v131
	v_readfirstlane_b32 s29, v137
	s_nop 1
	v_subrev_u32_e32 v126, s44, v126
	v_subrev_u32_e32 v128, s44, v128
	v_subrev_u32_e32 v130, s30, v130
	s_add_u32 s44, s44, 0xc0
	s_addc_u32 s45, s45, 0
	s_add_u32 s30, s30, 0xc0
	s_addc_u32 s31, s31, 0
	v_bfe_u32 v2, v10, 2, 2
	v_and_b32_e32 v139, 1, v136
	v_xor_b32_e32 v2, v135, v2
	v_lshlrev_b32_e32 v3, 6, v138
	v_ashrrev_i32_e32 v0, 7, v10
	v_lshl_or_b32 v2, v2, 4, v3
	v_lshlrev_b32_e32 v3, 12, v139
	s_movk_i32 s8, 0x4000
	s_waitcnt vmcnt(9)
	v_mov_b32_e32 v19, 0
	v_mov_b32_e32 v20, 0
	v_mov_b32_e32 v21, 0
	v_mov_b32_e32 v30, 0
	v_mov_b32_e32 v31, 0
	v_mov_b32_e32 v32, 0
	v_mov_b32_e32 v33, 0
	v_mov_b32_e32 v35, 0
	v_mov_b32_e32 v36, 0
	v_mov_b32_e32 v37, 0
	v_mov_b32_e32 v38, 0
	v_mov_b32_e32 v39, 0
	v_mov_b32_e32 v40, 0
	v_mov_b32_e32 v41, 0
	v_mov_b32_e32 v42, 0
	v_mov_b32_e32 v43, 0
	v_mov_b32_e32 v44, 0
	v_mov_b32_e32 v45, 0
	v_mov_b32_e32 v46, 0
	v_mov_b32_e32 v47, 0
	v_mov_b32_e32 v48, 0
	v_mov_b32_e32 v49, 0
	v_mov_b32_e32 v50, 0
	v_mov_b32_e32 v51, 0
	v_mov_b32_e32 v52, 0
	v_mov_b32_e32 v53, 0
	v_mov_b32_e32 v54, 0
	v_mov_b32_e32 v55, 0
	v_mov_b32_e32 v56, 0
	v_mov_b32_e32 v57, 0
	v_mov_b32_e32 v58, 0
	v_mov_b32_e32 v59, 0
	v_mov_b32_e32 v60, 0
	v_mov_b32_e32 v61, 0
	v_mov_b32_e32 v62, 0
	v_mov_b32_e32 v63, 0
	v_mov_b32_e32 v64, 0
	v_mov_b32_e32 v65, 0
	v_mov_b32_e32 v66, 0
	v_mov_b32_e32 v67, 0
	v_mov_b32_e32 v68, 0
	v_mov_b32_e32 v69, 0
	v_mov_b32_e32 v70, 0
	v_mov_b32_e32 v71, 0
	v_mov_b32_e32 v72, 0
	v_mov_b32_e32 v73, 0
	v_mov_b32_e32 v74, 0
	v_mov_b32_e32 v75, 0
	v_mov_b32_e32 v76, 0
	v_mov_b32_e32 v77, 0
	v_mov_b32_e32 v78, 0
	v_mov_b32_e32 v79, 0
	v_mov_b32_e32 v80, 0
	v_mov_b32_e32 v81, 0
	v_mov_b32_e32 v82, 0
	v_mov_b32_e32 v83, 0
	v_mov_b32_e32 v84, 0
	v_mov_b32_e32 v85, 0
	v_mov_b32_e32 v86, 0
	v_mov_b32_e32 v87, 0
	v_mov_b32_e32 v88, 0
	v_mov_b32_e32 v89, 0
	v_mov_b32_e32 v90, 0
	v_mov_b32_e32 v91, 0
	v_mov_b32_e32 v92, 0
	v_mov_b32_e32 v93, 0
	v_mov_b32_e32 v94, 0
	v_mov_b32_e32 v95, 0
	v_mov_b32_e32 v96, 0
	v_mov_b32_e32 v97, 0
	v_mov_b32_e32 v98, 0
	v_mov_b32_e32 v99, 0
	v_mov_b32_e32 v100, 0
	v_mov_b32_e32 v101, 0
	v_mov_b32_e32 v102, 0
	v_mov_b32_e32 v103, 0
	v_mov_b32_e32 v104, 0
	v_mov_b32_e32 v105, 0
	s_waitcnt vmcnt(6)
	v_lshl_or_b32 v140, v0, 12, v2
	v_or3_b32 v141, v3, v2, s8
	s_waitcnt lgkmcnt(0)
	s_barrier
	ds_read_b128 v[2:5], v140
	ds_read_b128 v[6:9], v140 offset:1024
	ds_read_b128 v[10:13], v140 offset:2048
	ds_read_b128 v[14:17], v140 offset:3072
	ds_read_b128 v[26:29], v141
	ds_read_b128 v[22:25], v141 offset:1024
	v_cmp_lt_i32_e32 vcc, 3, v136
	s_and_saveexec_b64 s[20:21], vcc
	s_cbranch_execz .LBB0_289
	s_barrier

.LBB0_403:
	s_andn2_b64 vcc, exec, s[22:23]
	s_cbranch_vccnz .LBB0_428
	v_readlane_b32 s22, v254, 44
	v_readlane_b32 s23, v254, 45
	s_andn2_b64 vcc, exec, s[22:23]
	s_cbranch_vccnz .LBB0_428
	v_mov_b32_e32 v8, v202
	v_readlane_b32 s8, v254, 48
	v_bfe_u32 v201, v8, 4, 2
	v_bitop3_b32 v0, v201, v8, 3 bitop3:0x78
	v_bfe_u32 v4, v8, 2, 4
	v_lshlrev_b32_e32 v0, 4, v0
	v_ashrrev_i32_e32 v230, 6, v8
	v_or_b32_e32 v9, s8, v4
	v_lshl_add_u64 v[2:3], s[20:21], 0, v[0:1]
	v_readlane_b32 s8, v254, 46
	v_readlane_b32 s20, v254, 55
	v_readlane_b32 s21, v254, 56
	v_or_b32_e32 v10, s8, v4
	v_cmp_gt_i32_e32 vcc, 16, v230
	v_lshl_add_u64 v[4:5], s[20:21], 0, v[0:1]
	v_lshlrev_b32_e32 v0, 4, v230
	v_cndmask_b32_e32 v11, v9, v10, vcc
	v_cndmask_b32_e32 v7, v3, v5, vcc
	v_cndmask_b32_e32 v6, v2, v4, vcc
	v_add_u32_e32 v11, v11, v0
	v_cmp_gt_i32_e32 vcc, 8, v230
	v_mad_i64_i32 v[126:127], s[20:21], v11, s84, v[6:7]
	s_nop 0
	v_cndmask_b32_e32 v11, v9, v10, vcc
	s_movk_i32 s8, 0x80
	v_cndmask_b32_e32 v7, v3, v5, vcc
	v_cndmask_b32_e32 v6, v2, v4, vcc
	v_add3_u32 v11, v0, v11, s8
	v_cmp_gt_i32_e32 vcc, 0, v230
	v_mad_i64_i32 v[128:129], s[20:21], v11, s84, v[6:7]
	s_nop 0
	v_cndmask_b32_e32 v6, v9, v10, vcc
	s_movk_i32 s8, 0x100
	v_and_b32_e32 v200, 63, v8
	v_cndmask_b32_e32 v3, v3, v5, vcc
	v_cndmask_b32_e32 v2, v2, v4, vcc
	v_add3_u32 v0, v0, v6, s8
	v_mad_i64_i32 v[130:131], s[20:21], v0, s84, v[2:3]
	v_lshlrev_b32_e32 v0, 4, v200
	v_lshl_or_b32 v232, v230, 10, v0
	v_add_u32_e32 v0, 0x2000, v232
	v_readfirstlane_b32 s8, v232
	s_mov_b32 m0, s8
	v_readfirstlane_b32 s8, v0
	v_add_u32_e32 v0, 0x4000, v232
	s_barrier
	global_load_lds_dwordx4 v[126:127], off
	s_mov_b32 m0, s8
	v_readfirstlane_b32 s8, v0
	v_add_u32_e32 v0, 0x6000, v232
	global_load_lds_dwordx4 v[128:129], off
	s_mov_b32 m0, s8
	v_readfirstlane_b32 s8, v0
	v_add_u32_e32 v0, 0x8000, v232
	global_load_lds_dwordx4 v[130:131], off
	v_lshl_add_u64 v[2:3], v[126:127], 0, 64
	s_mov_b32 m0, s8
	v_readfirstlane_b32 s8, v0
	v_add_u32_e32 v0, 0xa000, v232
	global_load_lds_dwordx4 v[2:3], off
	v_lshl_add_u64 v[2:3], v[128:129], 0, 64
	s_mov_b32 m0, s8
	v_readfirstlane_b32 s8, v0
	v_add_u32_e32 v0, 0xc000, v232
	global_load_lds_dwordx4 v[2:3], off
	v_lshl_add_u64 v[2:3], v[130:131], 0, 64
	s_mov_b32 m0, s8
	v_readfirstlane_b32 s8, v0
	v_add_u32_e32 v0, 0xe000, v232
	global_load_lds_dwordx4 v[2:3], off
	v_lshl_add_u64 v[2:3], v[126:127], 0, s[10:11]
	s_mov_b32 m0, s8
	v_readfirstlane_b32 s8, v0
	v_add_u32_e32 v0, 0x10000, v232
	global_load_lds_dwordx4 v[2:3], off
	v_lshl_add_u64 v[2:3], v[128:129], 0, s[10:11]
	s_mov_b32 m0, s8
	v_readfirstlane_b32 s8, v0
	global_load_lds_dwordx4 v[2:3], off
	v_lshl_add_u64 v[2:3], v[130:131], 0, s[10:11]
	s_mov_b32 m0, s8
	v_and_b32_e32 v234, 15, v8
	global_load_lds_dwordx4 v[2:3], off
	v_readfirstlane_b32 s90, v126
	v_readfirstlane_b32 s91, v127
	v_readfirstlane_b32 s92, v130
	v_readfirstlane_b32 s93, v131
	v_readfirstlane_b32 s88, v232
	s_nop 1
	v_subrev_u32_e32 v126, s90, v126
	v_subrev_u32_e32 v128, s90, v128
	v_subrev_u32_e32 v130, s92, v130
	s_add_u32 s90, s90, 0xc0
	s_addc_u32 s91, s91, 0
	s_add_u32 s92, s92, 0xc0
	s_addc_u32 s93, s93, 0
	v_bfe_u32 v2, v8, 2, 2
	v_and_b32_e32 v231, 1, v230
	v_xor_b32_e32 v2, v201, v2
	v_lshlrev_b32_e32 v3, 6, v234
	v_ashrrev_i32_e32 v0, 7, v8
	v_lshl_or_b32 v2, v2, 4, v3
	v_lshlrev_b32_e32 v3, 12, v231
	s_movk_i32 s8, 0x4000
	s_waitcnt vmcnt(9)
	v_mov_b32_e32 v31, 0
	v_mov_b32_e32 v32, 0
	v_mov_b32_e32 v33, 0
	v_mov_b32_e32 v38, 0
	v_mov_b32_e32 v39, 0
	v_mov_b32_e32 v40, 0
	v_mov_b32_e32 v41, 0
	v_mov_b32_e32 v43, 0
	v_mov_b32_e32 v44, 0
	v_mov_b32_e32 v45, 0
	v_mov_b32_e32 v46, 0
	v_mov_b32_e32 v47, 0
	v_mov_b32_e32 v48, 0
	v_mov_b32_e32 v49, 0
	v_mov_b32_e32 v50, 0
	v_mov_b32_e32 v51, 0
	v_mov_b32_e32 v52, 0
	v_mov_b32_e32 v53, 0
	v_mov_b32_e32 v54, 0
	v_mov_b32_e32 v55, 0
	v_mov_b32_e32 v56, 0
	v_mov_b32_e32 v57, 0
	v_mov_b32_e32 v58, 0
	v_mov_b32_e32 v59, 0
	v_mov_b32_e32 v60, 0
	v_mov_b32_e32 v61, 0
	v_mov_b32_e32 v62, 0
	v_mov_b32_e32 v63, 0
	v_mov_b32_e32 v64, 0
	v_mov_b32_e32 v65, 0
	v_mov_b32_e32 v66, 0
	v_mov_b32_e32 v67, 0
	v_mov_b32_e32 v68, 0
	v_mov_b32_e32 v69, 0
	v_mov_b32_e32 v70, 0
	v_mov_b32_e32 v71, 0
	v_mov_b32_e32 v72, 0
	v_mov_b32_e32 v73, 0
	v_mov_b32_e32 v74, 0
	v_mov_b32_e32 v75, 0
	v_mov_b32_e32 v76, 0
	v_mov_b32_e32 v77, 0
	v_mov_b32_e32 v78, 0
	v_mov_b32_e32 v79, 0
	v_mov_b32_e32 v80, 0
	v_mov_b32_e32 v81, 0
	v_mov_b32_e32 v82, 0
	v_mov_b32_e32 v83, 0
	v_mov_b32_e32 v84, 0
	v_mov_b32_e32 v85, 0
	v_mov_b32_e32 v86, 0
	v_mov_b32_e32 v87, 0
	v_mov_b32_e32 v88, 0
	v_mov_b32_e32 v89, 0
	v_mov_b32_e32 v90, 0
	v_mov_b32_e32 v91, 0
	v_mov_b32_e32 v92, 0
	v_mov_b32_e32 v93, 0
	v_mov_b32_e32 v94, 0
	v_mov_b32_e32 v95, 0
	v_mov_b32_e32 v96, 0
	v_mov_b32_e32 v97, 0
	v_mov_b32_e32 v98, 0
	v_mov_b32_e32 v99, 0
	v_mov_b32_e32 v100, 0
	v_mov_b32_e32 v101, 0
	v_mov_b32_e32 v102, 0
	v_mov_b32_e32 v103, 0
	v_mov_b32_e32 v104, 0
	v_mov_b32_e32 v105, 0
	v_mov_b32_e32 v134, 0
	v_mov_b32_e32 v135, 0
	v_mov_b32_e32 v136, 0
	v_mov_b32_e32 v137, 0
	v_mov_b32_e32 v138, 0
	v_mov_b32_e32 v139, 0
	v_mov_b32_e32 v140, 0
	v_mov_b32_e32 v141, 0
	v_mov_b32_e32 v142, 0
	v_mov_b32_e32 v143, 0
	v_mov_b32_e32 v144, 0
	v_mov_b32_e32 v145, 0
	v_mov_b32_e32 v146, 0
	v_mov_b32_e32 v147, 0
	v_mov_b32_e32 v148, 0
	v_mov_b32_e32 v149, 0
	v_mov_b32_e32 v150, 0
	v_mov_b32_e32 v151, 0
	v_mov_b32_e32 v152, 0
	v_mov_b32_e32 v153, 0
	v_mov_b32_e32 v154, 0
	v_mov_b32_e32 v155, 0
	v_mov_b32_e32 v156, 0
	v_mov_b32_e32 v157, 0
	v_mov_b32_e32 v158, 0
	v_mov_b32_e32 v159, 0
	v_mov_b32_e32 v160, 0
	v_mov_b32_e32 v161, 0
	v_mov_b32_e32 v162, 0
	v_mov_b32_e32 v163, 0
	v_mov_b32_e32 v164, 0
	v_mov_b32_e32 v165, 0
	v_mov_b32_e32 v166, 0
	v_mov_b32_e32 v167, 0
	v_mov_b32_e32 v168, 0
	v_mov_b32_e32 v169, 0
	v_mov_b32_e32 v170, 0
	v_mov_b32_e32 v171, 0
	v_mov_b32_e32 v172, 0
	v_mov_b32_e32 v173, 0
	v_mov_b32_e32 v174, 0
	v_mov_b32_e32 v175, 0
	v_mov_b32_e32 v176, 0
	v_mov_b32_e32 v177, 0
	v_mov_b32_e32 v178, 0
	v_mov_b32_e32 v179, 0
	v_mov_b32_e32 v180, 0
	v_mov_b32_e32 v181, 0
	v_mov_b32_e32 v182, 0
	v_mov_b32_e32 v183, 0
	v_mov_b32_e32 v184, 0
	v_mov_b32_e32 v185, 0
	v_mov_b32_e32 v186, 0
	v_mov_b32_e32 v187, 0
	v_mov_b32_e32 v188, 0
	v_mov_b32_e32 v189, 0
	v_mov_b32_e32 v190, 0
	v_mov_b32_e32 v191, 0
	v_mov_b32_e32 v192, 0
	v_mov_b32_e32 v193, 0
	v_mov_b32_e32 v194, 0
	v_mov_b32_e32 v195, 0
	v_mov_b32_e32 v196, 0
	v_mov_b32_e32 v197, 0
	s_waitcnt vmcnt(6)
	v_lshl_or_b32 v235, v0, 12, v2
	v_or3_b32 v236, v3, v2, s8
	s_waitcnt lgkmcnt(0)
	s_barrier
	ds_read_b128 v[14:17], v235
	ds_read_b128 v[10:13], v235 offset:1024
	ds_read_b128 v[6:9], v235 offset:2048
	ds_read_b128 v[2:5], v235 offset:3072
	ds_read_b128 v[26:29], v236
	ds_read_b128 v[18:21], v236 offset:1024
	v_cmp_lt_i32_e32 vcc, 3, v230
	s_and_saveexec_b64 s[20:21], vcc
	s_cbranch_execz .LBB0_407
	s_barrier
.LBB0_407:
	s_or_b64 exec, exec, s[20:21]
	v_readlane_b32 s8, v254, 46
	v_mov_b32_e32 v24, v1
	v_mov_b32_e32 v25, v1
	v_lshl_add_u32 v233, v0, 6, s8
	v_lshrrev_b32_e32 v0, 4, v233
	s_movk_i32 s8, 0xc0
	v_mul_lo_u32 v238, v0, s8
	v_lshlrev_b32_e32 v0, 3, v200
	v_mov_b32_e32 v22, v1
	v_mov_b32_e32 v23, v1
	v_mov_b32_e32 v30, 0
	v_mov_b32_e32 v42, 0
	v_mov_b64_e32 v[36:37], v[24:25]
	v_add_u32_e32 v237, 0x800, v236
	v_or_b32_e32 v239, 0xc0, v238
	v_add_u32_e32 v240, 0x180, v238
	v_add_u32_e32 v241, 0x240, v238
	s_mov_b32 s8, 3
	v_lshl_add_u64 v[132:133], s[46:47], 0, v[0:1]
	s_mov_b64 s[20:21], 0
	v_mov_b64_e32 v[34:35], v[22:23]
	s_branch .LBB0_409

.LBB0_641:
	s_lshl_b32 s19, s17, 6
	s_and_b32 s19, s19, 0x1f00
	v_mov_b32_e32 v200, v202
	s_add_i32 s20, s19, 0xffffff00
	v_bfe_u32 v186, v200, 2, 4
	v_bfe_u32 v197, v200, 4, 2
	v_or_b32_e32 v10, s20, v186
	v_readlane_b32 s20, v254, 46
	v_ashrrev_i32_e32 v187, 6, v200
	v_bitop3_b32 v0, v197, v200, 3 bitop3:0x78
	v_or_b32_e32 v11, s20, v186
	v_readlane_b32 s20, v254, 49
	v_lshlrev_b32_e32 v0, 4, v0
	v_readlane_b32 s21, v254, 50
	v_cmp_gt_i32_e32 vcc, 16, v187
	v_lshl_add_u64 v[2:3], s[44:45], 0, v[0:1]
	v_lshl_add_u64 v[4:5], s[20:21], 0, v[0:1]
	v_lshlrev_b32_e32 v0, 4, v187
	v_cndmask_b32_e32 v8, v10, v11, vcc
	v_add_u32_e32 v8, v8, v0
	v_ashrrev_i32_e32 v9, 31, v8
	v_cndmask_b32_e32 v7, v3, v5, vcc
	v_cndmask_b32_e32 v6, v2, v4, vcc
	v_lshlrev_b64 v[8:9], 11, v[8:9]
	v_cmp_gt_i32_e32 vcc, 8, v187
	v_lshl_add_u64 v[188:189], v[6:7], 0, v[8:9]
	s_movk_i32 s20, 0x80
	v_cndmask_b32_e32 v8, v10, v11, vcc
	v_add3_u32 v8, v0, v8, s20
	v_ashrrev_i32_e32 v9, 31, v8
	v_cndmask_b32_e32 v7, v3, v5, vcc
	v_cndmask_b32_e32 v6, v2, v4, vcc
	v_lshlrev_b64 v[8:9], 11, v[8:9]
	v_cmp_gt_i32_e32 vcc, 0, v187
	v_lshl_add_u64 v[190:191], v[6:7], 0, v[8:9]
	s_movk_i32 s20, 0x100
	v_cndmask_b32_e32 v8, v10, v11, vcc
	v_add3_u32 v8, v0, v8, s20
	v_ashrrev_i32_e32 v9, 31, v8
	v_cndmask_b32_e32 v7, v3, v5, vcc
	v_cndmask_b32_e32 v6, v2, v4, vcc
	v_lshlrev_b64 v[8:9], 11, v[8:9]
	v_cmp_gt_i32_e32 vcc, -8, v187
	v_lshl_add_u64 v[192:193], v[6:7], 0, v[8:9]
	s_movk_i32 s20, 0x180
	v_cndmask_b32_e32 v6, v10, v11, vcc
	v_and_b32_e32 v196, 63, v200
	v_cndmask_b32_e32 v2, v2, v4, vcc
	v_add3_u32 v4, v0, v6, s20
	v_cndmask_b32_e32 v3, v3, v5, vcc
	v_ashrrev_i32_e32 v5, 31, v4
	v_lshlrev_b32_e32 v198, 4, v196
	v_lshlrev_b64 v[4:5], 11, v[4:5]
	v_lshl_or_b32 v0, v187, 10, v198
	v_lshl_add_u64 v[194:195], v[2:3], 0, v[4:5]
	v_readfirstlane_b32 s20, v0
	v_add_u32_e32 v2, 0x2000, v0
	s_mov_b32 m0, s20
	v_readfirstlane_b32 s20, v2
	v_add_u32_e32 v2, 0x4000, v0
	s_waitcnt lgkmcnt(0)
	s_barrier
	global_load_lds_dwordx4 v[188:189], off
	s_mov_b32 m0, s20
	v_readfirstlane_b32 s20, v2
	v_add_u32_e32 v2, 0x6000, v0
	global_load_lds_dwordx4 v[190:191], off
	s_mov_b32 m0, s20
	v_readfirstlane_b32 s20, v2
	v_add_u32_e32 v4, 0x8000, v0
	global_load_lds_dwordx4 v[192:193], off
	s_mov_b32 m0, s20
	v_readfirstlane_b32 s20, v4
	v_add_u32_e32 v4, 0xa000, v0
	global_load_lds_dwordx4 v[194:195], off
	v_lshl_add_u64 v[2:3], v[188:189], 0, 64
	s_mov_b32 m0, s20
	v_readfirstlane_b32 s20, v4
	v_add_u32_e32 v4, 0xc000, v0
	global_load_lds_dwordx4 v[2:3], off
	v_lshl_add_u64 v[2:3], v[190:191], 0, 64
	s_mov_b32 m0, s20
	v_readfirstlane_b32 s20, v4
	v_add_u32_e32 v4, 0xe000, v0
	global_load_lds_dwordx4 v[2:3], off
	v_lshl_add_u64 v[2:3], v[192:193], 0, 64
	s_mov_b32 m0, s20
	v_readfirstlane_b32 s20, v4
	v_add_u32_e32 v4, 0x10000, v0
	global_load_lds_dwordx4 v[2:3], off
	v_lshl_add_u64 v[2:3], v[194:195], 0, 64
	s_mov_b32 m0, s20
	v_readfirstlane_b32 s20, v4
	v_add_u32_e32 v4, 0x12000, v0
	global_load_lds_dwordx4 v[2:3], off
	v_lshl_add_u64 v[2:3], v[188:189], 0, s[10:11]
	s_mov_b32 m0, s20
	v_readfirstlane_b32 s20, v4
	v_add_u32_e32 v4, 0x14000, v0
	global_load_lds_dwordx4 v[2:3], off
	v_lshl_add_u64 v[2:3], v[190:191], 0, s[10:11]
	s_mov_b32 m0, s20
	v_readfirstlane_b32 s20, v4
	v_add_u32_e32 v4, 0x16000, v0
	global_load_lds_dwordx4 v[2:3], off
	v_lshl_add_u64 v[2:3], v[192:193], 0, s[10:11]
	s_mov_b32 m0, s20
	v_readfirstlane_b32 s20, v4
	global_load_lds_dwordx4 v[2:3], off
	v_lshl_add_u64 v[2:3], v[194:195], 0, s[10:11]
	s_mov_b32 m0, s20
	v_and_b32_e32 v199, 15, v200
	global_load_lds_dwordx4 v[2:3], off
	v_readfirstlane_b32 s94, v188
	v_readfirstlane_b32 s95, v189
	v_readfirstlane_b32 s42, v192
	v_readfirstlane_b32 s43, v193
	v_readfirstlane_b32 s69, v0
	s_nop 1
	v_subrev_u32_e32 v188, s94, v188
	v_subrev_u32_e32 v190, s94, v190
	v_subrev_u32_e32 v192, s42, v192
	v_subrev_u32_e32 v194, s42, v194
	s_add_u32 s94, s94, 0xc0
	s_addc_u32 s95, s95, 0
	s_add_u32 s42, s42, 0xc0
	s_addc_u32 s43, s43, 0
	v_bfe_u32 v2, v200, 2, 2
	v_xor_b32_e32 v2, v197, v2
	v_lshlrev_b32_e32 v3, 6, v199
	v_ashrrev_i32_e32 v230, 7, v200
	v_and_b32_e32 v201, 1, v187
	v_lshl_or_b32 v2, v2, 4, v3
	s_waitcnt vmcnt(12)
	v_mov_b32_e32 v4, 0
	v_mov_b32_e32 v5, 0
	v_mov_b32_e32 v6, 0
	v_mov_b32_e32 v7, 0
	v_mov_b32_e32 v8, 0
	v_mov_b32_e32 v9, 0
	v_mov_b32_e32 v10, 0
	v_mov_b32_e32 v11, 0
	v_mov_b32_e32 v12, 0
	v_mov_b32_e32 v13, 0
	v_mov_b32_e32 v14, 0
	v_mov_b32_e32 v15, 0
	v_mov_b32_e32 v16, 0
	v_mov_b32_e32 v17, 0
	v_mov_b32_e32 v18, 0
	v_mov_b32_e32 v19, 0
	v_mov_b32_e32 v20, 0
	v_mov_b32_e32 v21, 0
	v_mov_b32_e32 v22, 0
	v_mov_b32_e32 v23, 0
	v_mov_b32_e32 v24, 0
	v_mov_b32_e32 v25, 0
	v_mov_b32_e32 v26, 0
	v_mov_b32_e32 v27, 0
	v_mov_b32_e32 v28, 0
	v_mov_b32_e32 v29, 0
	v_mov_b32_e32 v30, 0
	v_mov_b32_e32 v31, 0
	v_mov_b32_e32 v32, 0
	v_mov_b32_e32 v33, 0
	v_mov_b32_e32 v34, 0
	v_mov_b32_e32 v35, 0
	v_mov_b32_e32 v36, 0
	v_mov_b32_e32 v37, 0
	v_mov_b32_e32 v38, 0
	v_mov_b32_e32 v39, 0
	v_mov_b32_e32 v40, 0
	v_mov_b32_e32 v41, 0
	v_mov_b32_e32 v42, 0
	v_mov_b32_e32 v43, 0
	v_mov_b32_e32 v44, 0
	v_mov_b32_e32 v45, 0
	v_mov_b32_e32 v46, 0
	v_mov_b32_e32 v47, 0
	v_mov_b32_e32 v48, 0
	v_mov_b32_e32 v49, 0
	v_mov_b32_e32 v50, 0
	v_mov_b32_e32 v51, 0
	v_mov_b32_e32 v52, 0
	v_mov_b32_e32 v53, 0
	v_mov_b32_e32 v54, 0
	v_mov_b32_e32 v55, 0
	v_mov_b32_e32 v56, 0
	v_mov_b32_e32 v57, 0
	v_mov_b32_e32 v58, 0
	v_mov_b32_e32 v59, 0
	v_mov_b32_e32 v60, 0
	v_mov_b32_e32 v61, 0
	v_mov_b32_e32 v62, 0
	v_mov_b32_e32 v63, 0
	v_mov_b32_e32 v64, 0
	v_mov_b32_e32 v65, 0
	v_mov_b32_e32 v66, 0
	v_mov_b32_e32 v67, 0
	v_mov_b32_e32 v68, 0
	v_mov_b32_e32 v69, 0
	v_mov_b32_e32 v70, 0
	v_mov_b32_e32 v71, 0
	v_mov_b32_e32 v72, 0
	v_mov_b32_e32 v73, 0
	v_mov_b32_e32 v74, 0
	v_mov_b32_e32 v75, 0
	v_mov_b32_e32 v76, 0
	v_mov_b32_e32 v77, 0
	v_mov_b32_e32 v78, 0
	v_mov_b32_e32 v79, 0
	v_mov_b32_e32 v80, 0
	v_mov_b32_e32 v81, 0
	v_mov_b32_e32 v82, 0
	v_mov_b32_e32 v83, 0
	v_mov_b32_e32 v84, 0
	v_mov_b32_e32 v85, 0
	v_mov_b32_e32 v86, 0
	v_mov_b32_e32 v87, 0
	v_mov_b32_e32 v88, 0
	v_mov_b32_e32 v89, 0
	v_mov_b32_e32 v90, 0
	v_mov_b32_e32 v91, 0
	v_mov_b32_e32 v92, 0
	v_mov_b32_e32 v93, 0
	v_mov_b32_e32 v94, 0
	v_mov_b32_e32 v95, 0
	v_mov_b32_e32 v96, 0
	v_mov_b32_e32 v97, 0
	v_mov_b32_e32 v98, 0
	v_mov_b32_e32 v99, 0
	v_mov_b32_e32 v100, 0
	v_mov_b32_e32 v101, 0
	v_mov_b32_e32 v102, 0
	v_mov_b32_e32 v103, 0
	v_mov_b32_e32 v104, 0
	v_mov_b32_e32 v105, 0
	v_mov_b32_e32 v106, 0
	v_mov_b32_e32 v107, 0
	v_mov_b32_e32 v108, 0
	v_mov_b32_e32 v109, 0
	v_mov_b32_e32 v110, 0
	v_mov_b32_e32 v111, 0
	v_mov_b32_e32 v112, 0
	v_mov_b32_e32 v113, 0
	v_mov_b32_e32 v114, 0
	v_mov_b32_e32 v115, 0
	v_mov_b32_e32 v116, 0
	v_mov_b32_e32 v117, 0
	v_mov_b32_e32 v118, 0
	v_mov_b32_e32 v119, 0
	v_mov_b32_e32 v120, 0
	v_mov_b32_e32 v121, 0
	v_mov_b32_e32 v122, 0
	v_mov_b32_e32 v123, 0
	v_mov_b32_e32 v124, 0
	v_mov_b32_e32 v125, 0
	v_mov_b32_e32 v126, 0
	v_mov_b32_e32 v127, 0
	v_mov_b32_e32 v128, 0
	v_mov_b32_e32 v129, 0
	s_waitcnt vmcnt(8)
	v_lshl_or_b32 v231, v230, 12, v2
	v_lshlrev_b32_e32 v3, 13, v201
	s_movk_i32 s20, 0x4000
	s_waitcnt lgkmcnt(0)
	s_barrier
	ds_read_b128 v[130:133], v231
	ds_read_b128 v[134:137], v231 offset:1024
	ds_read_b128 v[138:141], v231 offset:2048
	ds_read_b128 v[142:145], v231 offset:3072
	v_or3_b32 v232, v3, v2, s20
	ds_read_b128 v[158:161], v232
	ds_read_b128 v[154:157], v232 offset:1024
	ds_read_b128 v[150:153], v232 offset:2048
	ds_read_b128 v[146:149], v232 offset:3072
	v_cmp_lt_i32_e32 vcc, 3, v187
	s_and_saveexec_b64 s[20:21], vcc
	s_cbranch_execz .LBB0_643
	s_barrier
.LBB0_643:
	s_or_b64 exec, exec, s[20:21]
	v_mov_b32_e32 v2, 0
	v_add_u32_e32 v233, 0x1000, v232
	s_mov_b32 s30, 0
	s_mov_b64 s[20:21], 0
	s_mov_b32 s31, 0x18000
	v_mov_b32_e32 v3, v2
	s_branch .LBB0_645
